# static priority raise: one s_setprio 1 for waves 4-7 during the attention chunk loops (reset to 0 afterwards), so the two waves of a SIMD de-phase MFMA and softmax VALU; on top of v64
# speedup vs baseline: 1.0035x; 1.0035x over previous
.LBB0_247:
	v_readfirstlane_b32 s98, v182
	s_nop 3
	s_lshr_b32 s98, s98, 6
	s_cmp_ge_u32 s98, 4
	s_cbranch_scc0 .Lprio_done_a
	s_setprio 1

.LBB0_250:
	v_add_u32_e32 v33, s52, v35
	v_lshlrev_b32_e32 v37, s48, v33
	v_lshl_add_u64 v[74:75], v[72:73], 1, s[4:5]
	v_add_u32_e32 v37, s49, v37
	v_mad_i64_i32 v[38:39], s[6:7], v37, s42, v[74:75]
	v_add_lshl_u32 v37, v33, 32, s48
	v_add_co_u32_e32 v42, vcc, s43, v38
	v_add_u32_e32 v37, s49, v37
	s_nop 0
	v_addc_co_u32_e32 v43, vcc, 0, v39, vcc
	v_mad_i64_i32 v[46:47], s[6:7], v37, s42, v[74:75]
	v_add_lshl_u32 v37, v33, 64, s48
	v_add_co_u32_e32 v48, vcc, s43, v46
	v_add_u32_e32 v37, s49, v37
	v_add_u32_e32 v33, 0x60, v33
	global_load_dwordx4 v[38:41], v[38:39], off offset:2048
	s_nop 0
	global_load_dwordx4 v[42:45], v[42:43], off
	v_addc_co_u32_e32 v49, vcc, 0, v47, vcc
	global_load_dwordx4 v[64:67], v[46:47], off offset:2048
	global_load_dwordx4 v[68:71], v[48:49], off
	v_mad_i64_i32 v[46:47], s[6:7], v37, s42, v[74:75]
	v_lshlrev_b32_e32 v33, s48, v33
	v_add_co_u32_e32 v48, vcc, s43, v46
	v_add_u32_e32 v33, s49, v33
	s_nop 0
	v_addc_co_u32_e32 v49, vcc, 0, v47, vcc
	global_load_dwordx4 v[76:79], v[46:47], off offset:2048
	global_load_dwordx4 v[84:87], v[48:49], off
	v_mad_i64_i32 v[46:47], s[6:7], v33, s42, v[74:75]
	v_add_co_u32_e32 v48, vcc, s43, v46
	s_ashr_i32 s10, s1, 2
	s_nop 0
	v_addc_co_u32_e32 v49, vcc, 0, v47, vcc
	global_load_dwordx4 v[88:91], v[46:47], off offset:2048
	global_load_dwordx4 v[92:95], v[48:49], off
	s_movk_i32 s6, 0x110
	v_mul_lo_u32 v33, v35, s6
	s_and_b32 s27, s10, -16
	v_readlane_b32 s7, v252, 37
	v_add3_u32 v83, 0, v32, v33
	v_add3_u32 v98, s39, v32, v33
	v_add3_u32 v99, s7, v32, v33
	v_or_b32_e32 v32, s27, v34
	v_add_u32_e32 v32, s52, v32
	v_lshlrev_b32_e32 v32, s48, v32
	v_bfe_u32 v37, v36, 4, 2
	v_mov_b64_e32 v[46:47], s[4:5]
	s_add_i32 s6, s2, 1
	v_add_u32_e32 v32, s49, v32
	v_mov_b32_e32 v97, v73
	v_lshlrev_b32_e32 v96, 4, v37
	v_cvt_f32_ubyte0_e32 v100, s6
	v_mad_i64_i32 v[32:33], s[6:7], v32, s42, v[46:47]
	s_waitcnt vmcnt(15)
	ds_write_b128 v83, v[4:7]
	s_waitcnt vmcnt(14)
	ds_write_b128 v83, v[0:3] offset:34816
	s_waitcnt vmcnt(13)
	ds_write_b128 v83, v[8:11] offset:8704
	s_waitcnt vmcnt(12)
	ds_write_b128 v83, v[12:15] offset:43520
	s_waitcnt vmcnt(11)
	ds_write_b128 v83, v[16:19] offset:17408
	s_waitcnt vmcnt(10)
	ds_write_b128 v83, v[20:23] offset:52224
	s_waitcnt vmcnt(9)
	ds_write_b128 v83, v[24:27] offset:26112
	s_waitcnt vmcnt(8)
	ds_write_b128 v83, v[28:31] offset:60928
	v_lshl_add_u64 v[32:33], v[32:33], 0, v[96:97]
	global_load_dwordx4 v[48:51], v[32:33], off
	global_load_dwordx4 v[52:55], v[32:33], off offset:64
	global_load_dwordx4 v[56:59], v[32:33], off offset:128
	global_load_dwordx4 v[60:63], v[32:33], off offset:192
	s_mov_b32 s6, 0x42fc0000
	v_cmp_lt_f32_e32 vcc, s6, v100
	s_and_b64 s[6:7], vcc, exec
	s_cselect_b32 s6, 0xffffffc0, 0
	s_ashr_i32 s20, s1, 7
	s_ashr_i32 s1, s0, 31
	s_lshl_b64 s[64:65], s[0:1], 14
	s_lshl_b32 s0, s8, 13
	s_or_b32 s95, s49, s0
	s_cmp_lt_i32 s20, 4
	s_cselect_b64 s[66:67], -1, 0
	v_cndmask_b32_e32 v32, 0, v80, vcc
	v_sub_f32_e32 v32, v32, v100
	v_exp_f32_e32 v32, v32
	v_cvt_f32_ubyte0_e32 v33, s9
	v_and_b32_e32 v36, 3, v36
	v_lshlrev_b32_e32 v72, 3, v37
	v_ldexp_f32 v32, v32, s6
	v_mul_f32_e32 v32, v32, v33
	v_lshrrev_b32_e32 v33, 2, v34
	v_mul_f32_e32 v32, 0x3fb8aa3b, v32
	v_cmp_eq_u32_e64 s[0:1], 0, v37
	s_movk_i32 s24, 0x81
	s_movk_i32 s30, 0x82
	s_movk_i32 s31, 0x83
	s_movk_i32 s33, 0x84
	s_movk_i32 s34, 0x85
	s_movk_i32 s36, 0x86
	s_movk_i32 s16, 0x87
	s_waitcnt vmcnt(11)
	ds_write_b128 v98, v[38:41]
	s_waitcnt vmcnt(9)
	ds_write_b128 v98, v[64:67] offset:8704
	s_waitcnt vmcnt(7)
	ds_write_b128 v98, v[76:79] offset:17408
	ds_write_b128 v99, v[42:45]
	ds_write_b128 v99, v[68:71] offset:8704
	s_waitcnt vmcnt(6)
	ds_write_b128 v99, v[84:87] offset:17408
	s_waitcnt vmcnt(5)
	ds_write_b128 v98, v[88:91] offset:26112
	s_waitcnt vmcnt(4)
	ds_write_b128 v99, v[92:95] offset:26112
	v_lshl_add_u64 v[76:77], s[4:5], 0, v[96:97]
	s_and_b32 s4, s20, 3
	s_add_i32 s5, s20, 1
	s_cmp_lt_i32 s20, 3
	s_cselect_b64 s[68:69], -1, 0
	s_and_b32 s97, s5, 3
	s_cmp_lt_i32 s20, 2
	s_mul_i32 s96, s4, 0x2200
	s_cselect_b64 s[70:71], -1, 0
	s_xor_b32 s62, s4, 2
	s_add_i32 s4, s20, -1
	s_cmp_lt_i32 s20, 1
	s_cselect_b64 s[72:73], -1, 0
	s_and_b32 s63, s4, 3
	s_cmp_lt_i32 s20, 0
	s_cselect_b64 s[76:77], -1, 0
	s_cmp_gt_i32 s20, 3
	s_cselect_b64 s[78:79], -1, 0
	s_cmp_gt_i32 s20, 2
	s_cselect_b64 s[80:81], -1, 0
	s_cmp_gt_i32 s20, 1
	v_lshl_or_b32 v38, v33, 3, v36
	v_and_b32_e32 v40, 64, v81
	s_cselect_b64 s[82:83], -1, 0
	s_cmp_gt_i32 s20, 0
	v_mul_u32_u24_e32 v38, 0x110, v38
	v_xor_b32_e32 v39, 16, v81
	v_add_u32_e32 v40, 64, v40
	s_cselect_b64 s[84:85], -1, 0
	s_cmp_gt_i32 s20, -1
	v_add3_u32 v84, 0, v38, v96
	v_and_or_b32 v38, s10, 16, v34
	v_cmp_lt_i32_e32 vcc, v39, v40
	s_cselect_b64 s[86:87], -1, 0
	s_lshl_b32 s26, s26, 1
	v_or_b32_e32 v38, 0x80, v38
	v_cndmask_b32_e32 v39, v81, v39, vcc
	s_add_u32 s28, s56, s26
	v_sub_u32_e32 v64, v38, v72
	v_lshlrev_b32_e32 v86, 2, v39
	v_xor_b32_e32 v39, 32, v81
	s_addc_u32 s29, s57, 0
	s_lshl_b32 s2, s2, 2
	v_readlane_b32 s26, v252, 34
	v_cvt_f32_ubyte0_e32 v38, v64
	v_cmp_lt_i32_e32 vcc, v39, v40
	v_or_b32_e32 v33, v72, v33
	s_add_u32 s88, s26, s2
	v_readlane_b32 s2, v252, 35
	v_mul_f32_e64 v85, -v32, v38
	v_cndmask_b32_e32 v39, v81, v39, vcc
	v_mul_u32_u24_e32 v33, 0x110, v33
	v_lshlrev_b32_e32 v36, 3, v36
	s_addc_u32 s89, s2, 0
	s_add_i32 s2, s52, s27
	v_lshlrev_b32_e32 v87, 2, v39
	v_add3_u32 v88, v36, s94, v33
	v_fma_f32 v89, 0, v32, v85
	v_fma_f32 v90, -v32, v38, v32
	v_fma_f32 v91, 2.0, v32, v85
	v_fmamk_f32 v92, v32, 0x40400000, v85
	v_fma_f32 v93, 4.0, v32, v85
	v_fmamk_f32 v94, v32, 0x40a00000, v85
	v_fmamk_f32 v95, v32, 0x40c00000, v85
	v_fmamk_f32 v96, v32, 0x40e00000, v85
	s_movk_i32 s18, 0x88
	v_fmamk_f32 v97, v32, 0x42000000, v85
	v_fmamk_f32 v98, v32, 0x42040000, v85
	v_fmamk_f32 v99, v32, 0x42080000, v85
	v_fmamk_f32 v100, v32, 0x420c0000, v85
	v_fmamk_f32 v101, v32, 0x42100000, v85
	v_fmamk_f32 v102, v32, 0x42140000, v85
	v_fmamk_f32 v103, v32, 0x42180000, v85
	v_fmamk_f32 v104, v32, 0x421c0000, v85
	v_fmamk_f32 v105, v32, 0x42800000, v85
	v_fmamk_f32 v106, v32, 0x42820000, v85
	v_fmamk_f32 v107, v32, 0x42840000, v85
	v_fmamk_f32 v108, v32, 0x42860000, v85
	v_fmamk_f32 v109, v32, 0x42880000, v85
	v_fmamk_f32 v110, v32, 0x428a0000, v85
	v_fmamk_f32 v111, v32, 0x428c0000, v85
	v_fmamk_f32 v112, v32, 0x428e0000, v85
	v_fmamk_f32 v113, v32, 0x42c00000, v85
	v_fmamk_f32 v114, v32, 0x42c20000, v85
	v_fmamk_f32 v115, v32, 0x42c40000, v85
	v_fmamk_f32 v116, v32, 0x42c60000, v85
	v_fmamk_f32 v117, v32, 0x42c80000, v85
	v_fmamk_f32 v118, v32, 0x42ca0000, v85
	v_fmamk_f32 v119, v32, 0x42cc0000, v85
	v_fmamk_f32 v120, v32, 0x42ce0000, v85
	v_fmamk_f32 v121, v32, 0x43000000, v85
	s_movk_i32 s20, 0x7f
	v_fmamk_f32 v122, v32, 0x43010000, v85
	s_movk_i32 s22, 0x80
	v_fmamk_f32 v123, v32, 0x43020000, v85
	v_fmamk_f32 v124, v32, 0x43030000, v85
	v_lshl_add_u64 v[78:79], s[28:29], 0, v[72:73]
	v_add_u32_e32 v72, s2, v34
	v_fmamk_f32 v125, v32, 0x43040000, v85
	v_fmamk_f32 v126, v32, 0x43050000, v85
	v_fmamk_f32 v127, v32, 0x43060000, v85
	v_fmac_f32_e32 v85, 0x43070000, v32
	v_add_u32_e32 v128, s52, v35
	s_waitcnt vmcnt(3)
	v_mov_b64_e32 v[32:33], v[48:49]
	s_waitcnt vmcnt(2)
	v_mov_b64_e32 v[36:37], v[52:53]
	s_waitcnt vmcnt(1)
	v_mov_b64_e32 v[40:41], v[56:57]
	s_waitcnt vmcnt(0)
	v_mov_b64_e32 v[44:45], v[60:61]
	s_mov_b32 s53, 1
	s_mov_b32 s3, 0
	s_mulk_i32 s97, 0x2200
	s_mulk_i32 s62, 0x2200
	s_mulk_i32 s63, 0x2200
	v_cmp_gt_u32_e64 s[4:5], s24, v64
	v_cmp_gt_u32_e64 s[6:7], s30, v64
	v_cmp_gt_u32_e64 s[8:9], s31, v64
	v_cmp_gt_u32_e64 s[10:11], s33, v64
	v_cmp_gt_u32_e64 s[12:13], s34, v64
	v_cmp_gt_u32_e64 s[14:15], s36, v64
	v_cmp_gt_u32_e64 s[16:17], s16, v64
	v_cmp_gt_u32_e64 s[18:19], s18, v64
	v_cmp_lt_u32_e64 s[20:21], s20, v64
	v_cmp_lt_u32_e64 s[22:23], s22, v64
	v_cmp_lt_u32_e64 s[24:25], s24, v64
	v_cmp_lt_u32_e64 s[26:27], s30, v64
	v_mov_b64_e32 v[34:35], v[50:51]
	v_mov_b64_e32 v[38:39], v[54:55]
	v_mov_b64_e32 v[42:43], v[58:59]
	v_mov_b64_e32 v[46:47], v[62:63]
	v_cmp_lt_u32_e64 s[28:29], s31, v64
	v_cmp_lt_u32_e64 s[30:31], s33, v64
	v_cmp_lt_u32_e64 s[34:35], s34, v64
	v_cmp_lt_u32_e64 s[36:37], s36, v64
	s_waitcnt lgkmcnt(0)
	s_barrier
	s_branch .LBB0_252
	s_nop 0
	s_nop 0
	s_nop 0
	s_nop 0
	s_nop 0
	s_nop 0
	s_nop 0
	s_nop 0
	s_nop 0
	s_nop 0
	s_nop 0
	s_nop 0
	s_nop 0
	s_nop 0
	s_nop 0
	s_nop 0
	s_nop 0
	s_nop 0
	s_nop 0
	s_nop 0
	s_nop 0
	s_nop 0
	s_nop 0
	s_nop 0
	s_nop 0
	s_nop 0
	s_nop 0
	s_nop 0
	s_nop 0
	s_nop 0
	s_nop 0
	s_nop 0
	s_nop 0
	s_nop 0
	s_nop 0
	s_nop 0
	s_nop 0
	s_nop 0
	s_nop 0
	s_nop 0
	s_nop 0
	s_nop 0
	s_nop 0
	s_nop 0
	s_nop 0
	s_nop 0
	s_nop 0
	s_nop 0
	s_nop 0
	s_nop 0
	s_nop 0
	s_nop 0
	s_nop 0
	s_nop 0
	s_nop 0
	s_nop 0
	s_nop 0
	s_nop 0

.LBB0_259:
	s_setprio 0
	v_readlane_b32 s2, v252, 8
	v_readlane_b32 s3, v252, 9
	s_andn2_b64 vcc, exec, s[2:3]
	s_nop 0
	v_cndmask_b32_e64 v0, 0, 1, s[2:3]
	v_cmp_ne_u32_e64 s[0:1], 1, v0
	s_nop 1
	v_writelane_b32 v252, s0, 35
	s_nop 1
	v_writelane_b32 v252, s1, 36
	s_cbranch_vccnz .LBB0_404
	s_add_u32 s52, s58, 0x14800000
	s_addc_u32 s53, s59, 0
	s_add_u32 s60, s58, 0x10000
	s_addc_u32 s61, s59, 0
	s_add_u32 s62, s58, 0x280000
	s_addc_u32 s63, s59, 0
	s_add_u32 s74, s58, 0x2c0000
	s_addc_u32 s75, s59, 0
	s_add_u32 s28, s58, 0x300000
	s_addc_u32 s29, s59, 0
	s_add_u32 s69, s58, 0x341000
	s_addc_u32 s80, s59, 0
	s_add_u32 s81, s58, 0x340000
	s_addc_u32 s82, s59, 0
	s_add_u32 s30, s58, 0x1a800000
	s_addc_u32 s31, s59, 0
	s_add_u32 s34, s58, 0x1c800000
	s_addc_u32 s35, s59, 0
	s_add_u32 s83, s58, 0x380000
	s_addc_u32 s84, s59, 0
	s_add_u32 s85, s56, 0x6000000
	v_readlane_b32 s0, v252, 0
	s_addc_u32 s86, s57, 0
	s_mov_b32 s37, 0
	v_mov_b32_e32 v181, 0x3ecc95a3
	s_add_i32 s87, 0, 0x217fc
	s_add_i32 s88, 0, 0x213fc
	v_mov_b32_e32 v129, 0
	s_add_i32 s89, 0, 0x21c00
	s_mov_b64 s[38:39], 0x2000
	s_mov_b64 s[64:65], 0x4000
	s_mov_b64 s[66:67], 0x6000
	s_movk_i32 s90, 0x1800
	s_mov_b32 s68, 0x3d800000
	s_movk_i32 s91, 0x210
	s_mov_b32 s92, 0x7fffe0
	s_add_i32 s93, 0, 0x18000
	s_mov_b64 s[70:71], 0x80
	s_add_i32 s94, 0, 0x1c000
	s_mov_b64 s[72:73], 0x100
	s_mov_b64 s[76:77], 0x180
	v_mov_b32_e32 v130, 0x3f317218
	v_mov_b32_e32 v148, 0x7f800000
	v_mov_b32_e32 v149, 0x7fc00000
	v_mov_b32_e32 v150, 0xff800000
	v_mov_b32_e32 v151, 1
	s_mov_b32 s78, s0
	s_branch .LBB0_262

.Lpadskip_3:
	s_branch .Lpadskip_4
	s_nop 0
	s_nop 0
	s_nop 0
	s_nop 0
	s_nop 0
	s_nop 0
	s_nop 0
	s_nop 0
	s_nop 0
	s_nop 0
	s_nop 0
	s_nop 0
	s_nop 0
	s_nop 0
	s_nop 0
	s_nop 0
	s_nop 0
	s_nop 0
	s_nop 0
	s_nop 0
	s_nop 0
	s_nop 0
	s_nop 0
	s_nop 0
	s_nop 0
	s_nop 0
	s_nop 0
	s_nop 0
	s_nop 0
	s_nop 0
	s_nop 0
	s_nop 0
	s_nop 0
	s_nop 0
	s_nop 0
	s_nop 0
	s_nop 0
	s_nop 0
	s_nop 0
	s_nop 0
	s_nop 0
	s_nop 0
	s_nop 0
	s_nop 0
	s_nop 0
	s_nop 0
	s_nop 0
	s_nop 0
	s_nop 0
	s_nop 0
	s_nop 0
	s_nop 0
	s_nop 0
	s_nop 0
	s_nop 0
	s_nop 0
	s_nop 0
	s_nop 0
	s_nop 0
	s_nop 0
	s_nop 0
	s_nop 0

.LBB0_410:
	v_add_u32_e32 v33, s52, v35
	v_lshlrev_b32_e32 v37, s48, v33
	v_lshl_add_u64 v[74:75], v[72:73], 1, s[6:7]
	v_add_u32_e32 v37, s49, v37
	v_mad_i64_i32 v[38:39], s[8:9], v37, s88, v[74:75]
	v_add_lshl_u32 v37, v33, 32, s48
	v_add_co_u32_e32 v42, vcc, s89, v38
	v_add_u32_e32 v37, s49, v37
	s_nop 0
	v_addc_co_u32_e32 v43, vcc, 0, v39, vcc
	v_mad_i64_i32 v[46:47], s[8:9], v37, s88, v[74:75]
	v_add_lshl_u32 v37, v33, 64, s48
	v_add_co_u32_e32 v48, vcc, s89, v46
	v_add_u32_e32 v37, s49, v37
	v_add_u32_e32 v33, 0x60, v33
	global_load_dwordx4 v[38:41], v[38:39], off offset:2048
	s_nop 0
	global_load_dwordx4 v[42:45], v[42:43], off
	v_addc_co_u32_e32 v49, vcc, 0, v47, vcc
	global_load_dwordx4 v[64:67], v[46:47], off offset:2048
	global_load_dwordx4 v[68:71], v[48:49], off
	v_mad_i64_i32 v[46:47], s[8:9], v37, s88, v[74:75]
	v_lshlrev_b32_e32 v33, s48, v33
	v_add_co_u32_e32 v48, vcc, s89, v46
	v_add_u32_e32 v33, s49, v33
	s_nop 0
	v_addc_co_u32_e32 v49, vcc, 0, v47, vcc
	global_load_dwordx4 v[76:79], v[46:47], off offset:2048
	global_load_dwordx4 v[84:87], v[48:49], off
	v_mad_i64_i32 v[46:47], s[8:9], v33, s88, v[74:75]
	v_add_co_u32_e32 v48, vcc, s89, v46
	s_ashr_i32 s10, s1, 2
	s_nop 0
	v_addc_co_u32_e32 v49, vcc, 0, v47, vcc
	global_load_dwordx4 v[88:91], v[46:47], off offset:2048
	global_load_dwordx4 v[92:95], v[48:49], off
	s_movk_i32 s8, 0x110
	v_mul_lo_u32 v33, v35, s8
	s_and_b32 s30, s10, -16
	v_add3_u32 v83, 0, v32, v33
	v_add3_u32 v98, s90, v32, v33
	v_add3_u32 v99, s91, v32, v33
	v_or_b32_e32 v32, s30, v34
	v_add_u32_e32 v32, s52, v32
	v_lshlrev_b32_e32 v32, s48, v32
	v_bfe_u32 v37, v36, 4, 2
	v_mov_b64_e32 v[46:47], s[6:7]
	s_add_i32 s8, s28, 1
	v_add_u32_e32 v32, s49, v32
	v_mov_b32_e32 v97, v73
	v_lshlrev_b32_e32 v96, 4, v37
	v_cvt_f32_ubyte0_e32 v100, s8
	v_mad_i64_i32 v[32:33], s[8:9], v32, s88, v[46:47]
	s_waitcnt vmcnt(15)
	ds_write_b128 v83, v[4:7]
	s_waitcnt vmcnt(14)
	ds_write_b128 v83, v[0:3] offset:34816
	s_waitcnt vmcnt(13)
	ds_write_b128 v83, v[8:11] offset:8704
	s_waitcnt vmcnt(12)
	ds_write_b128 v83, v[12:15] offset:43520
	s_waitcnt vmcnt(11)
	ds_write_b128 v83, v[16:19] offset:17408
	s_waitcnt vmcnt(10)
	ds_write_b128 v83, v[20:23] offset:52224
	s_waitcnt vmcnt(9)
	ds_write_b128 v83, v[24:27] offset:26112
	s_waitcnt vmcnt(8)
	ds_write_b128 v83, v[28:31] offset:60928
	v_lshl_add_u64 v[32:33], v[32:33], 0, v[96:97]
	global_load_dwordx4 v[48:51], v[32:33], off
	global_load_dwordx4 v[52:55], v[32:33], off offset:64
	global_load_dwordx4 v[56:59], v[32:33], off offset:128
	global_load_dwordx4 v[60:63], v[32:33], off offset:192
	s_mov_b32 s8, 0x42fc0000
	v_cmp_lt_f32_e32 vcc, s8, v100
	s_and_b64 s[8:9], vcc, exec
	s_cselect_b32 s8, 0xffffffc0, 0
	v_cvt_f32_ubyte0_e32 v33, s5
	s_ashr_i32 s5, s4, 31
	s_lshl_b32 s0, s0, 13
	s_ashr_i32 s22, s1, 7
	s_lshl_b64 s[44:45], s[4:5], 14
	s_or_b32 s96, s49, s0
	s_cmp_lt_i32 s22, 4
	s_cselect_b64 s[64:65], -1, 0
	s_and_b32 s1, s22, 3
	s_add_i32 s0, s22, 1
	s_cmp_lt_i32 s22, 3
	s_cselect_b64 s[66:67], -1, 0
	s_and_b32 s0, s0, 3
	v_cndmask_b32_e32 v32, 0, v80, vcc
	s_cmp_lt_i32 s22, 2
	v_sub_f32_e32 v32, v32, v100
	s_mul_i32 s97, s1, 0x2200
	s_cselect_b64 s[68:69], -1, 0
	s_xor_b32 s1, s1, 2
	v_exp_f32_e32 v32, v32
	v_and_b32_e32 v36, 3, v36
	v_lshlrev_b32_e32 v72, 3, v37
	v_cmp_eq_u32_e64 s[4:5], 0, v37
	v_ldexp_f32 v32, v32, s8
	v_mul_f32_e32 v32, v32, v33
	v_lshrrev_b32_e32 v33, 2, v34
	s_waitcnt vmcnt(11)
	ds_write_b128 v98, v[38:41]
	s_waitcnt vmcnt(9)
	ds_write_b128 v98, v[64:67] offset:8704
	s_waitcnt vmcnt(7)
	ds_write_b128 v98, v[76:79] offset:17408
	ds_write_b128 v99, v[42:45]
	ds_write_b128 v99, v[68:71] offset:8704
	s_waitcnt vmcnt(6)
	ds_write_b128 v99, v[84:87] offset:17408
	s_waitcnt vmcnt(5)
	ds_write_b128 v98, v[88:91] offset:26112
	s_waitcnt vmcnt(4)
	ds_write_b128 v99, v[92:95] offset:26112
	v_lshl_add_u64 v[76:77], s[6:7], 0, v[96:97]
	s_add_i32 s6, s22, -1
	s_cmp_lt_i32 s22, 1
	s_cselect_b64 s[70:71], -1, 0
	s_and_b32 s93, s6, 3
	s_cmp_lt_i32 s22, 0
	s_cselect_b64 s[72:73], -1, 0
	s_cmp_gt_i32 s22, 3
	s_cselect_b64 s[74:75], -1, 0
	s_cmp_gt_i32 s22, 2
	s_cselect_b64 s[76:77], -1, 0
	s_cmp_gt_i32 s22, 1
	v_lshl_or_b32 v38, v33, 3, v36
	v_and_b32_e32 v40, 64, v81
	s_cselect_b64 s[78:79], -1, 0
	s_cmp_gt_i32 s22, 0
	v_mul_u32_u24_e32 v38, 0x110, v38
	v_xor_b32_e32 v39, 16, v81
	v_add_u32_e32 v40, 64, v40
	s_cselect_b64 s[80:81], -1, 0
	s_cmp_gt_i32 s22, -1
	v_add3_u32 v84, 0, v38, v96
	v_and_or_b32 v38, s10, 16, v34
	v_cmp_lt_i32_e32 vcc, v39, v40
	s_cselect_b64 s[82:83], -1, 0
	s_lshl_b32 s29, s29, 1
	v_or_b32_e32 v38, 0x80, v38
	v_cndmask_b32_e32 v39, v81, v39, vcc
	s_add_u32 s34, s56, s29
	v_sub_u32_e32 v64, v38, v72
	v_lshlrev_b32_e32 v86, 2, v39
	v_xor_b32_e32 v39, 32, v81
	s_addc_u32 s35, s57, 0
	s_lshl_b32 s28, s28, 2
	v_mul_f32_e32 v32, 0x3fb8aa3b, v32
	v_cvt_f32_ubyte0_e32 v38, v64
	v_cmp_lt_i32_e32 vcc, v39, v40
	v_or_b32_e32 v33, v72, v33
	s_add_u32 s84, s50, s28
	v_mul_f32_e64 v85, -v32, v38
	v_cndmask_b32_e32 v39, v81, v39, vcc
	v_mul_u32_u24_e32 v33, 0x110, v33
	v_lshlrev_b32_e32 v36, 3, v36
	s_addc_u32 s85, s2, 0
	s_add_i32 s28, s52, s30
	v_lshlrev_b32_e32 v87, 2, v39
	v_add3_u32 v88, v36, s92, v33
	v_fma_f32 v89, 0, v32, v85
	s_movk_i32 s26, 0x81
	v_fma_f32 v90, -v32, v38, v32
	s_movk_i32 s31, 0x82
	v_fma_f32 v91, 2.0, v32, v85
	s_movk_i32 s33, 0x83
	v_fmamk_f32 v92, v32, 0x40400000, v85
	s_movk_i32 s36, 0x84
	v_fma_f32 v93, 4.0, v32, v85
	s_movk_i32 s37, 0x85
	v_fmamk_f32 v94, v32, 0x40a00000, v85
	s_movk_i32 s38, 0x86
	v_fmamk_f32 v95, v32, 0x40c00000, v85
	s_movk_i32 s18, 0x87
	v_fmamk_f32 v96, v32, 0x40e00000, v85
	s_movk_i32 s20, 0x88
	v_fmamk_f32 v97, v32, 0x42000000, v85
	v_fmamk_f32 v98, v32, 0x42040000, v85
	v_fmamk_f32 v99, v32, 0x42080000, v85
	v_fmamk_f32 v100, v32, 0x420c0000, v85
	v_fmamk_f32 v101, v32, 0x42100000, v85
	v_fmamk_f32 v102, v32, 0x42140000, v85
	v_fmamk_f32 v103, v32, 0x42180000, v85
	v_fmamk_f32 v104, v32, 0x421c0000, v85
	v_fmamk_f32 v105, v32, 0x42800000, v85
	v_fmamk_f32 v106, v32, 0x42820000, v85
	v_fmamk_f32 v107, v32, 0x42840000, v85
	v_fmamk_f32 v108, v32, 0x42860000, v85
	v_fmamk_f32 v109, v32, 0x42880000, v85
	v_fmamk_f32 v110, v32, 0x428a0000, v85
	v_fmamk_f32 v111, v32, 0x428c0000, v85
	v_fmamk_f32 v112, v32, 0x428e0000, v85
	v_fmamk_f32 v113, v32, 0x42c00000, v85
	v_fmamk_f32 v114, v32, 0x42c20000, v85
	v_fmamk_f32 v115, v32, 0x42c40000, v85
	v_fmamk_f32 v116, v32, 0x42c60000, v85
	v_fmamk_f32 v117, v32, 0x42c80000, v85
	v_fmamk_f32 v118, v32, 0x42ca0000, v85
	v_fmamk_f32 v119, v32, 0x42cc0000, v85
	v_fmamk_f32 v120, v32, 0x42ce0000, v85
	v_fmamk_f32 v121, v32, 0x43000000, v85
	s_movk_i32 s22, 0x7f
	v_fmamk_f32 v122, v32, 0x43010000, v85
	s_movk_i32 s24, 0x80
	v_fmamk_f32 v123, v32, 0x43020000, v85
	v_fmamk_f32 v124, v32, 0x43030000, v85
	v_lshl_add_u64 v[78:79], s[34:35], 0, v[72:73]
	v_add_u32_e32 v72, s28, v34
	v_fmamk_f32 v125, v32, 0x43040000, v85
	v_fmamk_f32 v126, v32, 0x43050000, v85
	v_fmamk_f32 v127, v32, 0x43060000, v85
	v_fmac_f32_e32 v85, 0x43070000, v32
	v_add_u32_e32 v128, s52, v35
	s_waitcnt vmcnt(3)
	v_mov_b64_e32 v[32:33], v[48:49]
	s_waitcnt vmcnt(2)
	v_mov_b64_e32 v[36:37], v[52:53]
	s_waitcnt vmcnt(1)
	v_mov_b64_e32 v[40:41], v[56:57]
	s_waitcnt vmcnt(0)
	v_mov_b64_e32 v[44:45], v[60:61]
	s_mov_b32 s53, 1
	s_mov_b32 s3, 0
	s_mulk_i32 s0, 0x2200
	s_mulk_i32 s1, 0x2200
	s_mulk_i32 s93, 0x2200
	v_cmp_gt_u32_e64 s[6:7], s26, v64
	v_cmp_gt_u32_e64 s[8:9], s31, v64
	v_cmp_gt_u32_e64 s[10:11], s33, v64
	v_cmp_gt_u32_e64 s[12:13], s36, v64
	v_cmp_gt_u32_e64 s[14:15], s37, v64
	v_cmp_gt_u32_e64 s[16:17], s38, v64
	v_cmp_gt_u32_e64 s[18:19], s18, v64
	v_cmp_gt_u32_e64 s[20:21], s20, v64
	v_cmp_lt_u32_e64 s[22:23], s22, v64
	v_cmp_lt_u32_e64 s[24:25], s24, v64
	v_cmp_lt_u32_e64 s[26:27], s26, v64
	v_cmp_lt_u32_e64 s[28:29], s31, v64
	v_mov_b64_e32 v[34:35], v[50:51]
	v_mov_b64_e32 v[38:39], v[54:55]
	v_mov_b64_e32 v[42:43], v[58:59]
	v_mov_b64_e32 v[46:47], v[62:63]
	v_cmp_lt_u32_e64 s[30:31], s33, v64
	v_cmp_lt_u32_e64 s[34:35], s36, v64
	v_cmp_lt_u32_e64 s[36:37], s37, v64
	v_cmp_lt_u32_e64 s[38:39], s38, v64
	s_waitcnt lgkmcnt(0)
	s_barrier
	s_branch .LBB0_412
	s_nop 0
	s_nop 0
	s_nop 0
	s_nop 0
	s_nop 0
	s_nop 0
	s_nop 0
	s_nop 0
	s_nop 0
	s_nop 0
	s_nop 0
	s_nop 0
	s_nop 0
	s_nop 0
	s_nop 0
	s_nop 0
	s_nop 0
	s_nop 0
	s_nop 0
	s_nop 0
	s_nop 0
	s_nop 0
	s_nop 0
	s_nop 0
	s_nop 0
	s_nop 0
	s_nop 0
	s_nop 0
	s_nop 0
	s_nop 0
	s_nop 0
	s_nop 0
	s_nop 0
	s_nop 0
	s_nop 0
	s_nop 0
	s_nop 0
	s_nop 0
	s_nop 0
	s_nop 0
	s_nop 0
	s_nop 0
	s_nop 0
	s_nop 0
	s_nop 0
	s_nop 0
	s_nop 0
	s_nop 0
	s_nop 0
	s_nop 0
	s_nop 0
	s_nop 0
	s_nop 0
	s_nop 0
	s_nop 0
	s_nop 0
	s_nop 0
	s_nop 0

.LBB0_419:
	s_setprio 0
	s_waitcnt vmcnt(0)
	s_waitcnt vmcnt(0) lgkmcnt(0)
	s_barrier
	s_mov_b64 s[4:5], exec
	v_readlane_b32 s0, v252, 1
	v_readlane_b32 s1, v252, 2
	v_readlane_b32 s42, v252, 27
	s_and_b64 s[0:1], s[4:5], s[0:1]
	v_readlane_b32 s43, v252, 28
	s_mov_b64 exec, s[0:1]
	s_cbranch_execz .LBB0_471
	s_add_i32 s0, 0, 0x26f00
	v_mov_b32_e32 v0, s0
	s_waitcnt vmcnt(0) expcnt(0) lgkmcnt(0)
	ds_read_b32 v2, v0
	s_add_i32 s0, 0, 0x26f04
	v_mov_b32_e32 v0, s0
	ds_read_b32 v0, v0
	s_waitcnt lgkmcnt(1)
	v_cmp_ne_u32_e32 vcc, 0, v2
	s_cbranch_vccnz .LBB0_435
	s_add_u32 s6, s58, 0xc200
	s_addc_u32 s7, s59, 0
	s_add_u32 s8, s58, 0xc400
	s_addc_u32 s9, s59, 0
	s_add_u32 s10, s58, 0xc500
	s_addc_u32 s11, s59, 0
	s_add_u32 s12, s58, 0xc600
	s_addc_u32 s13, s59, 0
	s_add_u32 s14, s58, 0xc700
	s_addc_u32 s15, s59, 0
	s_add_u32 s16, s58, 0xc800
	s_addc_u32 s17, s59, 0
	s_add_u32 s18, s58, 0xc900
	s_addc_u32 s19, s59, 0
	s_add_u32 s20, s58, 0xca00
	s_addc_u32 s21, s59, 0
	s_add_u32 s22, s58, 0xcb00
	s_addc_u32 s23, s59, 0
	s_add_u32 s24, s58, 0xcc00
	s_addc_u32 s25, s59, 0
	s_add_u32 s26, s58, 0xcd00
	s_addc_u32 s27, s59, 0
	s_add_u32 s28, s58, 0xce00
	s_addc_u32 s29, s59, 0
	s_add_u32 s30, s58, 0xcf00
	s_addc_u32 s31, s59, 0
	s_add_u32 s34, s58, 0xd000
	s_addc_u32 s35, s59, 0
	s_add_u32 s36, s58, 0xd100
	s_addc_u32 s37, s59, 0
	s_add_u32 s38, s58, 0xd200
	s_addc_u32 s39, s59, 0
	s_add_u32 s40, s58, 0xd300
	s_addc_u32 s41, s59, 0
	s_mov_b32 s0, 1
	v_mov_b32_e32 v16, 0
	s_branch .LBB0_423

.LBB0_677:
	s_or_b64 exec, exec, s[0:1]
	v_add_u32_e32 v46, 0xc0, v152
	s_waitcnt lgkmcnt(1)
	ds_read2st64_b32 v[44:45], v46 offset0:2 offset1:6
	s_waitcnt lgkmcnt(1)
	ds_read2st64_b32 v[46:47], v46 offset0:10 offset1:14
	ds_read_b32 v48, v174 offset:704
	ds_read_b32 v49, v175 offset:704
	ds_read_b32 v50, v176 offset:704
	s_waitcnt lgkmcnt(4)
	v_add_f32_e32 v44, v44, v45
	s_waitcnt lgkmcnt(3)
	v_add_f32_e32 v44, v44, v46
	v_add_f32_e32 v44, v44, v47
	s_waitcnt lgkmcnt(1)
	v_fmac_f32_e32 v44, v48, v49
	s_waitcnt lgkmcnt(0)
	v_max_f32_e32 v45, v50, v50
	v_max_f32_e64 v44, |v44|, v45
	v_rcp_f32_e32 v44, v44
	v_and_b32_e32 v50, 0xffff0000, v86
	v_mul_f32_e32 v50, 0xbfb8aa3b, v50
	v_exp_f32_e32 v51, v50
	v_pk_mul_f32 v[42:43], v[42:43], v[44:45] op_sel_hi:[1,0]
	v_pk_mul_f32 v[40:41], v[40:41], v[44:45] op_sel_hi:[1,0]
	v_pk_mul_f32 v[46:47], v[2:3], v[44:45] op_sel_hi:[1,0]
	v_pk_mul_f32 v[48:49], v[0:1], v[44:45] op_sel_hi:[1,0]
	v_lshlrev_b32_e32 v45, 16, v86
	v_mul_f32_e32 v45, 0xbfb8aa3b, v45
	v_exp_f32_e32 v45, v45
	v_lshlrev_b32_e32 v2, 16, v84
	v_and_b32_e32 v3, 0xffff0000, v84
	v_mul_f32_e32 v2, 0xbfb8aa3b, v2
	v_add_f32_e32 v45, 1.0, v45
	v_rcp_f32_e32 v50, v45
	v_add_f32_e32 v45, 1.0, v51
	v_lshlrev_b32_e32 v51, 16, v87
	v_mul_f32_e32 v51, 0xbfb8aa3b, v51
	v_exp_f32_e32 v52, v51
	v_and_b32_e32 v51, 0xffff0000, v87
	v_mul_f32_e32 v51, 0xbfb8aa3b, v51
	v_mul_f32_e32 v3, 0xbfb8aa3b, v3
	v_exp_f32_e32 v53, v51
	v_exp_f32_e32 v2, v2
	v_exp_f32_e32 v3, v3
	v_rcp_f32_e32 v51, v45
	v_add_f32_e32 v45, 1.0, v52
	v_rcp_f32_e32 v52, v45
	v_add_f32_e32 v45, 1.0, v53
	v_add_f32_e32 v0, 1.0, v2
	v_add_f32_e32 v1, 1.0, v3
	v_lshlrev_b32_e32 v2, 16, v85
	v_and_b32_e32 v3, 0xffff0000, v85
	v_rcp_f32_e32 v53, v45
	v_pk_mul_f32 v[84:85], v[50:51], v[48:49]
	v_pk_mul_f32 v[38:39], v[38:39], v[44:45] op_sel_hi:[1,0]
	v_pk_mul_f32 v[36:37], v[36:37], v[44:45] op_sel_hi:[1,0]
	v_pk_mul_f32 v[34:35], v[34:35], v[44:45] op_sel_hi:[1,0]
	v_lshlrev_b32_e32 v45, 16, v80
	v_and_b32_e32 v50, 0xffff0000, v80
	v_mul_f32_e32 v45, 0xbfb8aa3b, v45
	v_mul_f32_e32 v50, 0xbfb8aa3b, v50
	v_exp_f32_e32 v45, v45
	v_exp_f32_e32 v50, v50
	v_mul_f32_e32 v2, 0xbfb8aa3b, v2
	v_mul_f32_e32 v3, 0xbfb8aa3b, v3
	v_pk_mul_f32 v[76:77], v[52:53], v[46:47]
	v_pk_mul_f32 v[32:33], v[32:33], v[44:45] op_sel_hi:[1,0]
	v_add_f32_e32 v44, 1.0, v45
	v_add_f32_e32 v45, 1.0, v50
	v_lshlrev_b32_e32 v50, 16, v81
	v_and_b32_e32 v51, 0xffff0000, v81
	v_lshlrev_b32_e32 v52, 16, v82
	v_and_b32_e32 v53, 0xffff0000, v82
	v_exp_f32_e32 v2, v2
	v_exp_f32_e32 v3, v3
	v_mul_f32_e32 v50, 0xbfb8aa3b, v50
	v_mul_f32_e32 v51, 0xbfb8aa3b, v51
	v_mul_f32_e32 v52, 0xbfb8aa3b, v52
	v_mul_f32_e32 v53, 0xbfb8aa3b, v53
	v_exp_f32_e32 v50, v50
	v_exp_f32_e32 v51, v51
	v_exp_f32_e32 v52, v52
	v_exp_f32_e32 v53, v53
	v_lshlrev_b32_e32 v54, 16, v83
	v_and_b32_e32 v55, 0xffff0000, v83
	v_rcp_f32_e32 v0, v0
	v_rcp_f32_e32 v1, v1
	v_add_f32_e32 v2, 1.0, v2
	v_add_f32_e32 v3, 1.0, v3
	v_mul_f32_e32 v54, 0xbfb8aa3b, v54
	v_mul_f32_e32 v55, 0xbfb8aa3b, v55
	v_rcp_f32_e32 v2, v2
	v_rcp_f32_e32 v3, v3
	v_rcp_f32_e32 v44, v44
	v_rcp_f32_e32 v45, v45
	v_add_f32_e32 v50, 1.0, v50
	v_add_f32_e32 v51, 1.0, v51
	v_add_f32_e32 v52, 1.0, v52
	v_add_f32_e32 v53, 1.0, v53
	v_exp_f32_e32 v54, v54
	v_exp_f32_e32 v55, v55
	v_rcp_f32_e32 v50, v50
	v_rcp_f32_e32 v51, v51
	v_rcp_f32_e32 v52, v52
	v_rcp_f32_e32 v53, v53
	v_pk_mul_f32 v[0:1], v[0:1], v[40:41]
	v_pk_mul_f32 v[2:3], v[2:3], v[42:43]
	v_add_f32_e32 v40, v0, v1
	v_add_f32_e32 v54, 1.0, v54
	v_add_f32_e32 v55, 1.0, v55
	v_pk_mul_f32 v[82:83], v[44:45], v[36:37]
	v_add_f32_e32 v40, v2, v40
	v_rcp_f32_e32 v54, v54
	v_rcp_f32_e32 v55, v55
	v_pk_mul_f32 v[80:81], v[50:51], v[38:39]
	v_pk_mul_f32 v[74:75], v[52:53], v[32:33]
	v_add_f32_e32 v32, v82, v83
	v_add_f32_e32 v40, v3, v40
	v_add_f32_e32 v32, v80, v32
	v_add_f32_e32 v40, v84, v40
	v_add_f32_e32 v32, v81, v32
	v_add_f32_e32 v40, v85, v40
	v_add_f32_e32 v32, v74, v32
	v_add_f32_e32 v40, v76, v40
	v_pk_mul_f32 v[72:73], v[54:55], v[34:35]
	v_add_f32_e32 v32, v75, v32
	v_add_f32_e32 v40, v77, v40
	v_add_f32_e32 v32, v72, v32
	v_add_f32_e32 v56, 0, v40
	v_add_f32_e32 v32, v73, v32
	v_pk_mul_f32 v[40:41], v[0:1], v[0:1]
	v_add_f32_e32 v44, v32, v56
	v_pk_mul_f32 v[32:33], v[82:83], v[82:83]
	v_pk_mul_f32 v[42:43], v[2:3], v[2:3]
	v_pk_mul_f32 v[34:35], v[80:81], v[80:81]
	v_add_f32_e32 v32, v32, v33
	v_add_f32_e32 v33, v40, v41
	v_add_f32_e32 v32, v34, v32
	v_add_f32_e32 v33, v42, v33
	v_pk_mul_f32 v[46:47], v[84:85], v[84:85]
	v_pk_mul_f32 v[36:37], v[74:75], v[74:75]
	v_add_f32_e32 v32, v35, v32
	v_add_f32_e32 v33, v43, v33
	v_add_f32_e32 v32, v36, v32
	v_add_f32_e32 v33, v46, v33
	v_pk_mul_f32 v[48:49], v[76:77], v[76:77]
	v_pk_mul_f32 v[38:39], v[72:73], v[72:73]
	v_add_f32_e32 v32, v37, v32
	v_add_f32_e32 v33, v47, v33
	v_add_f32_e32 v32, v38, v32
	v_add_f32_e32 v33, v48, v33
	v_add_f32_e32 v32, v39, v32
	v_add_f32_e32 v33, v49, v33
	v_add_f32_e32 v35, v33, v32
	v_mov_b32_e32 v34, v44
	s_nop 1
	v_permlane16_swap_b32 v44, v34
	v_mov_b32_e32 v36, v35
	s_nop 1
	v_permlane16_swap_b32 v35, v36
	s_lshl_b64 s[0:1], s[20:21], 10
	s_waitcnt lgkmcnt(1)
	v_add_f32_e32 v32, v44, v34
	s_waitcnt lgkmcnt(0)
	v_add_f32_e32 v34, v35, v36
	v_mov_b32_e32 v33, v32
	s_nop 1
	v_permlane32_swap_b32 v32, v33
	v_mov_b32_e32 v35, v34
	s_nop 1
	v_permlane32_swap_b32 v34, v35
	s_and_saveexec_b64 s[20:21], vcc
	s_cbranch_execz .LBB0_614
	s_waitcnt lgkmcnt(1)
	v_add_f32_e32 v32, v32, v33
	s_waitcnt lgkmcnt(0)
	v_add_f32_e32 v33, v34, v35
	v_add_u32_e32 v34, 0xc0, v177
	ds_write2st64_b32 v34, v32, v33 offset0:2 offset1:18
	s_branch .LBB0_614
	s_nop 0
	s_nop 0
	s_nop 0
	s_nop 0
	s_nop 0
	s_nop 0
	s_nop 0
	s_nop 0
	s_nop 0
	s_nop 0
	s_nop 0
	s_nop 0
	s_nop 0
	s_nop 0
	s_nop 0
	s_nop 0
	s_nop 0
	s_nop 0
	s_nop 0
	s_nop 0
	s_nop 0
	s_nop 0
	s_nop 0
	s_nop 0
	s_nop 0
	s_nop 0
	s_nop 0
	s_nop 0
	s_nop 0
	s_nop 0
	s_nop 0
	s_nop 0
	s_nop 0
	s_nop 0
	s_nop 0
	s_nop 0
	s_nop 0
	s_nop 0
	s_nop 0
	s_nop 0
	s_nop 0
	s_nop 0
	s_nop 0
	s_nop 0
	s_nop 0
	s_nop 0
	s_nop 0
	s_nop 0
	s_nop 0
	s_nop 0
	s_nop 0
	s_nop 0
	s_nop 0
	s_nop 0
	s_nop 0
	s_nop 0
	s_nop 0
	s_nop 0
	s_nop 0
	s_nop 0
	s_nop 0
	s_nop 0
	s_nop 0
	s_nop 0
	s_nop 0
	s_nop 0
	s_nop 0
	s_nop 0
	s_nop 0
	s_nop 0
	s_nop 0
	s_nop 0
	s_nop 0
	s_nop 0
	s_nop 0
	s_nop 0
	s_nop 0
	s_nop 0
	s_nop 0
	s_nop 0
	s_nop 0
	s_nop 0
	s_nop 0
	s_nop 0
	s_nop 0
	s_nop 0
	s_nop 0
	s_nop 0
	s_nop 0
	s_nop 0
	s_nop 0
	s_nop 0
	s_nop 0
	s_nop 0
	s_nop 0
	s_nop 0
	s_nop 0
	s_nop 0
	s_nop 0
	s_nop 0
	s_nop 0
	s_nop 0
	s_nop 0
	s_nop 0
	s_nop 0
	s_nop 0
	s_nop 0
	s_nop 0
	s_nop 0
	s_nop 0
	s_nop 0
	s_nop 0
	s_nop 0
